# residual GEMM epilogues (phase 2 and 8 instances): XN 8-byte store pairs merged into 16-byte stores via v_permlane16_swap, counted vmcnt waits re-derived for the removed stores
# speedup vs baseline: 1.0059x; 1.0008x over previous
.LBB0_144:
	s_or_b64 exec, exec, s[24:25]
	s_waitcnt vmcnt(17)
	v_pk_add_f32 v[46:47], v[46:47], v[110:111]
	v_pk_add_f32 v[44:45], v[44:45], v[108:109]
	s_waitcnt lgkmcnt(0)
	v_lshlrev_b64 v[48:49], 11, v[120:121]
	global_store_dwordx4 v[122:123], v[44:47], off
	v_cvt_pk_bf16_f32 v248, v44, v45
	v_lshl_add_u64 v[48:49], v[48:49], 0, v[182:183]
	v_mul_f32_e32 v45, v45, v45
	v_fmac_f32_e32 v45, v44, v44
	v_mul_f32_e32 v44, v47, v47
	v_cvt_pk_bf16_f32 v249, v46, v47
	v_lshl_add_u64 v[48:49], v[48:49], 1, s[12:13]
	v_lshl_add_u64 v[48:49], v[48:49], 0, v[252:253]
	v_fmac_f32_e32 v44, v46, v46
	s_waitcnt vmcnt(17)
	v_pk_add_f32 v[42:43], v[42:43], v[106:107]
	v_pk_add_f32 v[40:41], v[40:41], v[104:105]
	v_add_f32_e32 v46, v45, v44
	global_store_dwordx4 v[122:123], v[40:43], off offset:64
	v_cvt_pk_bf16_f32 v250, v40, v41
	s_waitcnt vmcnt(17)
	v_pk_add_f32 v[38:39], v[38:39], v[102:103]
	v_mul_f32_e32 v41, v41, v41
	v_fmac_f32_e32 v41, v40, v40
	v_mul_f32_e32 v40, v43, v43
	v_fmac_f32_e32 v40, v42, v42
	v_pk_add_f32 v[36:37], v[36:37], v[100:101]
	v_cvt_pk_bf16_f32 v251, v42, v43
	v_add_f32_e32 v40, v41, v40
	v_mul_f32_e32 v41, v37, v37
	v_mul_f32_e32 v42, v39, v39
	v_fmac_f32_e32 v41, v36, v36
	v_fmac_f32_e32 v42, v38, v38
	v_add_f32_e32 v40, v46, v40
	v_add_f32_e32 v41, v41, v42
	s_nop 1
	v_permlane16_swap_b32_e32 v248, v250
	v_permlane16_swap_b32_e32 v249, v251
	global_store_dwordx4 v[48:49], v[248:251], off
	s_nop 1
	v_add_f32_e32 v44, v40, v41
	s_waitcnt vmcnt(17)
	v_pk_add_f32 v[42:43], v[34:35], v[98:99]
	v_pk_add_f32 v[40:41], v[32:33], v[96:97]
	v_mul_f32_e32 v33, v43, v43
	v_mul_f32_e32 v32, v41, v41
	v_fmac_f32_e32 v32, v40, v40
	v_fmac_f32_e32 v33, v42, v42
	v_add_f32_e32 v32, v32, v33
	v_add_f32_e32 v34, v44, v32
	ds_bpermute_b32 v35, v126, v34
	v_cvt_pk_bf16_f32 v248, v36, v37
	v_cvt_pk_bf16_f32 v249, v38, v39
	global_store_dwordx4 v[122:123], v[36:39], off offset:512
	s_waitcnt lgkmcnt(0)
	v_add_f32_e32 v32, v34, v35
	ds_bpermute_b32 v33, v127, v32
	v_cvt_pk_bf16_f32 v250, v40, v41
	v_cvt_pk_bf16_f32 v251, v42, v43
	global_store_dwordx4 v[122:123], v[40:43], off offset:576
	s_nop 1
	v_permlane16_swap_b32_e32 v248, v250
	v_permlane16_swap_b32_e32 v249, v251
	global_store_dwordx4 v[48:49], v[248:251], off offset:256
	s_nop 1
	s_and_saveexec_b64 s[24:25], s[6:7]
	s_cbranch_execz .LBB0_146
	v_lshl_add_u64 v[34:35], v[120:121], 2, s[80:81]
	s_waitcnt lgkmcnt(0)
	v_add_f32_e32 v32, v32, v33
	global_atomic_add_f32 v[34:35], v32, off
.LBB0_146:
	s_or_b64 exec, exec, s[24:25]
	s_waitcnt vmcnt(19)
	v_pk_add_f32 v[30:31], v[30:31], v[94:95]
	v_pk_add_f32 v[28:29], v[28:29], v[92:93]
	s_waitcnt lgkmcnt(0)
	v_lshlrev_b64 v[32:33], 11, v[116:117]
	global_store_dwordx4 v[118:119], v[28:31], off
	v_cvt_pk_bf16_f32 v248, v28, v29
	v_lshl_add_u64 v[32:33], v[32:33], 0, v[182:183]
	v_mul_f32_e32 v29, v29, v29
	v_fmac_f32_e32 v29, v28, v28
	v_mul_f32_e32 v28, v31, v31
	v_cvt_pk_bf16_f32 v249, v30, v31
	v_lshl_add_u64 v[32:33], v[32:33], 1, s[12:13]
	v_lshl_add_u64 v[32:33], v[32:33], 0, v[252:253]
	v_fmac_f32_e32 v28, v30, v30
	s_waitcnt vmcnt(19)
	v_pk_add_f32 v[26:27], v[26:27], v[90:91]
	v_pk_add_f32 v[24:25], v[24:25], v[88:89]
	v_add_f32_e32 v30, v29, v28
	global_store_dwordx4 v[118:119], v[24:27], off offset:64
	v_cvt_pk_bf16_f32 v250, v24, v25
	s_waitcnt vmcnt(19)
	v_pk_add_f32 v[22:23], v[22:23], v[86:87]
	v_mul_f32_e32 v25, v25, v25
	v_fmac_f32_e32 v25, v24, v24
	v_mul_f32_e32 v24, v27, v27
	v_fmac_f32_e32 v24, v26, v26
	v_pk_add_f32 v[20:21], v[20:21], v[84:85]
	v_cvt_pk_bf16_f32 v251, v26, v27
	v_add_f32_e32 v24, v25, v24
	v_mul_f32_e32 v25, v21, v21
	v_mul_f32_e32 v26, v23, v23
	v_fmac_f32_e32 v25, v20, v20
	v_fmac_f32_e32 v26, v22, v22
	v_add_f32_e32 v24, v30, v24
	v_add_f32_e32 v25, v25, v26
	s_nop 1
	v_permlane16_swap_b32_e32 v248, v250
	v_permlane16_swap_b32_e32 v249, v251
	global_store_dwordx4 v[32:33], v[248:251], off
	s_nop 1
	v_add_f32_e32 v28, v24, v25
	s_waitcnt vmcnt(19)
	v_pk_add_f32 v[26:27], v[18:19], v[82:83]
	v_pk_add_f32 v[24:25], v[16:17], v[80:81]
	v_mul_f32_e32 v17, v27, v27
	v_mul_f32_e32 v16, v25, v25
	v_fmac_f32_e32 v16, v24, v24
	v_fmac_f32_e32 v17, v26, v26
	v_add_f32_e32 v16, v16, v17
	v_add_f32_e32 v18, v28, v16
	ds_bpermute_b32 v19, v126, v18
	v_cvt_pk_bf16_f32 v248, v20, v21
	v_cvt_pk_bf16_f32 v249, v22, v23
	global_store_dwordx4 v[118:119], v[20:23], off offset:512
	s_waitcnt lgkmcnt(0)
	v_add_f32_e32 v16, v18, v19
	ds_bpermute_b32 v17, v127, v16
	v_cvt_pk_bf16_f32 v250, v24, v25
	v_cvt_pk_bf16_f32 v251, v26, v27
	global_store_dwordx4 v[118:119], v[24:27], off offset:576
	s_nop 1
	v_permlane16_swap_b32_e32 v248, v250
	v_permlane16_swap_b32_e32 v249, v251
	global_store_dwordx4 v[32:33], v[248:251], off offset:256
	s_nop 1
	s_and_saveexec_b64 s[24:25], s[6:7]
	s_cbranch_execz .LBB0_148
	v_lshl_add_u64 v[18:19], v[116:117], 2, s[80:81]
	s_waitcnt lgkmcnt(0)
	v_add_f32_e32 v16, v16, v17
	global_atomic_add_f32 v[18:19], v16, off
.LBB0_148:
	s_or_b64 exec, exec, s[24:25]
	s_waitcnt vmcnt(21)
	v_pk_add_f32 v[14:15], v[14:15], v[78:79]
	v_pk_add_f32 v[12:13], v[12:13], v[76:77]
	s_waitcnt lgkmcnt(0)
	v_lshlrev_b64 v[16:17], 11, v[112:113]
	global_store_dwordx4 v[114:115], v[12:15], off
	v_cvt_pk_bf16_f32 v248, v12, v13
	v_lshl_add_u64 v[16:17], v[16:17], 0, v[182:183]
	v_mul_f32_e32 v13, v13, v13
	v_fmac_f32_e32 v13, v12, v12
	v_mul_f32_e32 v12, v15, v15
	v_cvt_pk_bf16_f32 v249, v14, v15
	v_lshl_add_u64 v[16:17], v[16:17], 1, s[12:13]
	v_lshl_add_u64 v[16:17], v[16:17], 0, v[252:253]
	v_fmac_f32_e32 v12, v14, v14
	s_waitcnt vmcnt(21)
	v_pk_add_f32 v[10:11], v[10:11], v[74:75]
	v_pk_add_f32 v[8:9], v[8:9], v[72:73]
	v_add_f32_e32 v14, v13, v12
	global_store_dwordx4 v[114:115], v[8:11], off offset:64
	v_cvt_pk_bf16_f32 v250, v8, v9
	s_waitcnt vmcnt(21)
	v_pk_add_f32 v[6:7], v[6:7], v[70:71]
	v_mul_f32_e32 v9, v9, v9
	v_fmac_f32_e32 v9, v8, v8
	v_mul_f32_e32 v8, v11, v11
	v_fmac_f32_e32 v8, v10, v10
	v_pk_add_f32 v[4:5], v[4:5], v[68:69]
	v_cvt_pk_bf16_f32 v251, v10, v11
	v_add_f32_e32 v8, v9, v8
	v_mul_f32_e32 v9, v5, v5
	v_mul_f32_e32 v10, v7, v7
	v_fmac_f32_e32 v9, v4, v4
	v_fmac_f32_e32 v10, v6, v6
	v_add_f32_e32 v8, v14, v8
	v_add_f32_e32 v9, v9, v10
	s_nop 1
	v_permlane16_swap_b32_e32 v248, v250
	v_permlane16_swap_b32_e32 v249, v251
	global_store_dwordx4 v[16:17], v[248:251], off
	s_nop 1
	v_add_f32_e32 v12, v8, v9
	s_waitcnt vmcnt(21)
	v_pk_add_f32 v[10:11], v[2:3], v[66:67]
	v_pk_add_f32 v[8:9], v[0:1], v[64:65]
	v_mul_f32_e32 v1, v11, v11
	v_mul_f32_e32 v0, v9, v9
	v_fmac_f32_e32 v0, v8, v8
	v_fmac_f32_e32 v1, v10, v10
	v_add_f32_e32 v0, v0, v1
	v_add_f32_e32 v2, v12, v0
	ds_bpermute_b32 v3, v126, v2
	v_cvt_pk_bf16_f32 v248, v4, v5
	v_cvt_pk_bf16_f32 v249, v6, v7
	global_store_dwordx4 v[114:115], v[4:7], off offset:512
	s_waitcnt lgkmcnt(0)
	v_add_f32_e32 v0, v2, v3
	ds_bpermute_b32 v1, v127, v0
	v_cvt_pk_bf16_f32 v250, v8, v9
	v_cvt_pk_bf16_f32 v251, v10, v11
	global_store_dwordx4 v[114:115], v[8:11], off offset:576
	s_nop 1
	v_permlane16_swap_b32_e32 v248, v250
	v_permlane16_swap_b32_e32 v249, v251
	global_store_dwordx4 v[16:17], v[248:251], off offset:256
	s_nop 1
	s_and_saveexec_b64 s[24:25], s[6:7]
	s_cbranch_execz .LBB0_150
	v_lshl_add_u64 v[2:3], v[112:113], 2, s[80:81]
	s_waitcnt lgkmcnt(0)
	v_add_f32_e32 v0, v0, v1
	global_atomic_add_f32 v[2:3], v0, off

.LBB0_496:
	v_bfe_u32 v252, v244, 4, 1
	v_mul_u32_u24_e32 v252, 24, v252
	v_mov_b32_e32 v253, 0
	v_lshl_add_u32 v186, s79, 8, v194
	v_lshl_or_b32 v182, s80, 8, v196
	v_ashrrev_i32_e32 v183, 31, v182
	v_ashrrev_i32_e32 v187, 31, v186
	v_lshl_add_u64 v[184:185], v[182:183], 2, s[24:25]
	v_lshlrev_b64 v[120:121], 13, v[186:187]
	v_lshl_add_u64 v[120:121], v[184:185], 0, v[120:121]
	global_load_dwordx4 v[212:215], v[120:121], off
	global_load_dwordx4 v[216:219], v[120:121], off offset:64
	global_load_dwordx4 v[220:223], v[120:121], off offset:512
	global_load_dwordx4 v[224:227], v[120:121], off offset:576
	v_or_b32_e32 v192, 16, v186
	v_ashrrev_i32_e32 v193, 31, v192
	v_lshlrev_b64 v[120:121], 13, v[192:193]
	v_or_b32_e32 v190, 32, v186
	v_lshl_add_u64 v[120:121], v[184:185], 0, v[120:121]
	v_ashrrev_i32_e32 v191, 31, v190
	global_load_dwordx4 v[172:175], v[120:121], off
	global_load_dwordx4 v[168:171], v[120:121], off offset:64
	global_load_dwordx4 v[164:167], v[120:121], off offset:512
	global_load_dwordx4 v[160:163], v[120:121], off offset:576
	v_lshlrev_b64 v[120:121], 13, v[190:191]
	v_or_b32_e32 v188, 48, v186
	v_lshl_add_u64 v[120:121], v[184:185], 0, v[120:121]
	v_ashrrev_i32_e32 v189, 31, v188
	global_load_dwordx4 v[156:159], v[120:121], off
	global_load_dwordx4 v[152:155], v[120:121], off offset:64
	global_load_dwordx4 v[144:147], v[120:121], off offset:512
	global_load_dwordx4 v[128:131], v[120:121], off offset:576
	v_lshlrev_b64 v[120:121], 13, v[188:189]
	v_lshl_add_u64 v[120:121], v[184:185], 0, v[120:121]
	global_load_dwordx4 v[148:151], v[120:121], off
	global_load_dwordx4 v[140:143], v[120:121], off offset:64
	global_load_dwordx4 v[124:127], v[120:121], off offset:512
	s_nop 0
	global_load_dwordx4 v[120:123], v[120:121], off offset:576
	v_lshlrev_b64 v[228:229], 11, v[186:187]
	v_lshl_add_u64 v[228:229], v[228:229], 0, v[182:183]
	s_waitcnt vmcnt(0)
	v_pk_fma_f32 v[138:139], v[138:139], 0.5, v[214:215] op_sel_hi:[1,0,1]
	v_pk_fma_f32 v[136:137], v[136:137], 0.5, v[212:213] op_sel_hi:[1,0,1]
	v_lshl_add_u64 v[212:213], v[228:229], 2, s[12:13]
	global_store_dwordx4 v[212:213], v[136:139], off
	v_cvt_pk_bf16_f32 v248, v136, v137
	v_cvt_pk_bf16_f32 v249, v138, v139
	v_mul_f32_e32 v137, v137, v137
	v_fmac_f32_e32 v137, v136, v136
	v_mul_f32_e32 v136, v139, v139
	v_lshl_add_u64 v[228:229], v[228:229], 1, s[16:17]
	v_lshl_add_u64 v[228:229], v[228:229], 0, v[252:253]
	v_fmac_f32_e32 v136, v138, v138
	v_pk_fma_f32 v[134:135], v[134:135], 0.5, v[218:219] op_sel_hi:[1,0,1]
	v_pk_fma_f32 v[132:133], v[132:133], 0.5, v[216:217] op_sel_hi:[1,0,1]
	v_add_f32_e32 v138, v137, v136
	global_store_dwordx4 v[212:213], v[132:135], off offset:64
	v_cvt_pk_bf16_f32 v250, v132, v133
	v_cvt_pk_bf16_f32 v251, v134, v135
	v_mul_f32_e32 v133, v133, v133
	v_fmac_f32_e32 v133, v132, v132
	v_mul_f32_e32 v132, v135, v135
	v_fmac_f32_e32 v132, v134, v134
	v_add_f32_e32 v132, v133, v132
	v_pk_fma_f32 v[118:119], v[118:119], 0.5, v[222:223] op_sel_hi:[1,0,1]
	v_pk_fma_f32 v[116:117], v[116:117], 0.5, v[220:221] op_sel_hi:[1,0,1]
	s_nop 1
	v_permlane16_swap_b32_e32 v248, v250
	v_permlane16_swap_b32_e32 v249, v251
	global_store_dwordx4 v[228:229], v[248:251], off
	s_nop 1
	v_add_f32_e32 v134, v138, v132
	global_store_dwordx4 v[212:213], v[116:119], off offset:512
	v_cvt_pk_bf16_f32 v248, v116, v117
	v_cvt_pk_bf16_f32 v249, v118, v119
	v_mul_f32_e32 v117, v117, v117
	v_fmac_f32_e32 v117, v116, v116
	v_mul_f32_e32 v116, v119, v119
	v_fmac_f32_e32 v116, v118, v118
	v_add_f32_e32 v116, v117, v116
	v_pk_fma_f32 v[114:115], v[114:115], 0.5, v[226:227] op_sel_hi:[1,0,1]
	v_pk_fma_f32 v[112:113], v[112:113], 0.5, v[224:225] op_sel_hi:[1,0,1]
	v_add_f32_e32 v118, v134, v116
	global_store_dwordx4 v[212:213], v[112:115], off offset:576
	v_cvt_pk_bf16_f32 v250, v112, v113
	v_cvt_pk_bf16_f32 v251, v114, v115
	v_mul_f32_e32 v113, v113, v113
	v_fmac_f32_e32 v113, v112, v112
	v_mul_f32_e32 v112, v115, v115
	v_fmac_f32_e32 v112, v114, v114
	v_and_b32_e32 v114, 64, v244
	v_add_f32_e32 v112, v113, v112
	v_xor_b32_e32 v113, 16, v244
	v_add_u32_e32 v114, 64, v114
	v_cmp_lt_i32_e32 vcc, v113, v114
	v_add_f32_e32 v112, v118, v112
	s_nop 1
	v_permlane16_swap_b32_e32 v248, v250
	v_permlane16_swap_b32_e32 v249, v251
	global_store_dwordx4 v[228:229], v[248:251], off offset:256
	s_nop 1
	v_cndmask_b32_e32 v113, v244, v113, vcc
	v_lshlrev_b32_e32 v132, 2, v113
	ds_bpermute_b32 v113, v132, v112
	s_waitcnt lgkmcnt(0)
	v_add_f32_e32 v112, v112, v113
	v_xor_b32_e32 v113, 32, v244
	v_cmp_lt_i32_e32 vcc, v113, v114
	s_nop 1
	v_cndmask_b32_e32 v113, v244, v113, vcc
	v_lshlrev_b32_e32 v133, 2, v113
	ds_bpermute_b32 v113, v133, v112
	s_and_saveexec_b64 s[28:29], s[6:7]
	s_cbranch_execz .LBB0_498
	v_lshl_add_u64 v[114:115], v[186:187], 2, s[22:23]
	s_waitcnt lgkmcnt(0)
	v_add_f32_e32 v112, v112, v113
	global_atomic_add_f32 v[114:115], v112, off
.LBB0_498:
	s_or_b64 exec, exec, s[28:29]
	s_waitcnt lgkmcnt(0)
	v_lshlrev_b64 v[112:113], 11, v[192:193]
	v_lshl_add_u64 v[112:113], v[112:113], 0, v[182:183]
	v_pk_fma_f32 v[110:111], v[110:111], 0.5, v[174:175] op_sel_hi:[1,0,1]
	v_pk_fma_f32 v[108:109], v[108:109], 0.5, v[172:173] op_sel_hi:[1,0,1]
	v_lshl_add_u64 v[114:115], v[112:113], 2, s[12:13]
	global_store_dwordx4 v[114:115], v[108:111], off
	v_cvt_pk_bf16_f32 v248, v108, v109
	v_cvt_pk_bf16_f32 v249, v110, v111
	v_mul_f32_e32 v109, v109, v109
	v_fmac_f32_e32 v109, v108, v108
	v_mul_f32_e32 v108, v111, v111
	v_lshl_add_u64 v[112:113], v[112:113], 1, s[16:17]
	v_lshl_add_u64 v[112:113], v[112:113], 0, v[252:253]
	v_fmac_f32_e32 v108, v110, v110
	v_pk_fma_f32 v[106:107], v[106:107], 0.5, v[170:171] op_sel_hi:[1,0,1]
	v_pk_fma_f32 v[104:105], v[104:105], 0.5, v[168:169] op_sel_hi:[1,0,1]
	v_add_f32_e32 v110, v109, v108
	global_store_dwordx4 v[114:115], v[104:107], off offset:64
	v_cvt_pk_bf16_f32 v250, v104, v105
	v_pk_fma_f32 v[102:103], v[102:103], 0.5, v[166:167] op_sel_hi:[1,0,1]
	v_mul_f32_e32 v105, v105, v105
	v_fmac_f32_e32 v105, v104, v104
	v_mul_f32_e32 v104, v107, v107
	v_fmac_f32_e32 v104, v106, v106
	v_pk_fma_f32 v[100:101], v[100:101], 0.5, v[164:165] op_sel_hi:[1,0,1]
	v_cvt_pk_bf16_f32 v251, v106, v107
	v_add_f32_e32 v104, v105, v104
	v_mul_f32_e32 v105, v101, v101
	v_mul_f32_e32 v106, v103, v103
	v_fmac_f32_e32 v105, v100, v100
	v_fmac_f32_e32 v106, v102, v102
	v_add_f32_e32 v104, v110, v104
	v_add_f32_e32 v105, v105, v106
	s_nop 1
	v_permlane16_swap_b32_e32 v248, v250
	v_permlane16_swap_b32_e32 v249, v251
	global_store_dwordx4 v[112:113], v[248:251], off
	s_nop 1
	v_add_f32_e32 v108, v104, v105
	v_pk_fma_f32 v[106:107], v[98:99], 0.5, v[162:163] op_sel_hi:[1,0,1]
	v_pk_fma_f32 v[104:105], v[96:97], 0.5, v[160:161] op_sel_hi:[1,0,1]
	v_mul_f32_e32 v97, v107, v107
	v_mul_f32_e32 v96, v105, v105
	v_fmac_f32_e32 v96, v104, v104
	v_fmac_f32_e32 v97, v106, v106
	v_add_f32_e32 v96, v96, v97
	v_add_f32_e32 v98, v108, v96
	ds_bpermute_b32 v99, v132, v98
	v_cvt_pk_bf16_f32 v248, v100, v101
	v_cvt_pk_bf16_f32 v249, v102, v103
	global_store_dwordx4 v[114:115], v[100:103], off offset:512
	s_waitcnt lgkmcnt(0)
	v_add_f32_e32 v96, v98, v99
	ds_bpermute_b32 v97, v133, v96
	v_cvt_pk_bf16_f32 v250, v104, v105
	v_cvt_pk_bf16_f32 v251, v106, v107
	global_store_dwordx4 v[114:115], v[104:107], off offset:576
	s_nop 1
	v_permlane16_swap_b32_e32 v248, v250
	v_permlane16_swap_b32_e32 v249, v251
	global_store_dwordx4 v[112:113], v[248:251], off offset:256
	s_nop 1
	s_and_saveexec_b64 s[28:29], s[6:7]
	s_cbranch_execz .LBB0_500
	v_lshl_add_u64 v[98:99], v[192:193], 2, s[22:23]
	s_waitcnt lgkmcnt(0)
	v_add_f32_e32 v96, v96, v97
	global_atomic_add_f32 v[98:99], v96, off
.LBB0_500:
	s_or_b64 exec, exec, s[28:29]
	s_waitcnt lgkmcnt(0)
	v_lshlrev_b64 v[96:97], 11, v[190:191]
	v_lshl_add_u64 v[96:97], v[96:97], 0, v[182:183]
	v_pk_fma_f32 v[94:95], v[94:95], 0.5, v[158:159] op_sel_hi:[1,0,1]
	v_pk_fma_f32 v[92:93], v[92:93], 0.5, v[156:157] op_sel_hi:[1,0,1]
	v_lshl_add_u64 v[98:99], v[96:97], 2, s[12:13]
	global_store_dwordx4 v[98:99], v[92:95], off
	v_cvt_pk_bf16_f32 v248, v92, v93
	v_cvt_pk_bf16_f32 v249, v94, v95
	v_mul_f32_e32 v93, v93, v93
	v_fmac_f32_e32 v93, v92, v92
	v_mul_f32_e32 v92, v95, v95
	v_lshl_add_u64 v[96:97], v[96:97], 1, s[16:17]
	v_lshl_add_u64 v[96:97], v[96:97], 0, v[252:253]
	v_fmac_f32_e32 v92, v94, v94
	v_pk_fma_f32 v[90:91], v[90:91], 0.5, v[154:155] op_sel_hi:[1,0,1]
	v_pk_fma_f32 v[88:89], v[88:89], 0.5, v[152:153] op_sel_hi:[1,0,1]
	v_add_f32_e32 v94, v93, v92
	global_store_dwordx4 v[98:99], v[88:91], off offset:64
	v_cvt_pk_bf16_f32 v250, v88, v89
	v_pk_fma_f32 v[86:87], v[86:87], 0.5, v[146:147] op_sel_hi:[1,0,1]
	v_mul_f32_e32 v89, v89, v89
	v_fmac_f32_e32 v89, v88, v88
	v_mul_f32_e32 v88, v91, v91
	v_fmac_f32_e32 v88, v90, v90
	v_pk_fma_f32 v[84:85], v[84:85], 0.5, v[144:145] op_sel_hi:[1,0,1]
	v_cvt_pk_bf16_f32 v251, v90, v91
	v_add_f32_e32 v88, v89, v88
	v_mul_f32_e32 v89, v85, v85
	v_mul_f32_e32 v90, v87, v87
	v_fmac_f32_e32 v89, v84, v84
	v_fmac_f32_e32 v90, v86, v86
	v_add_f32_e32 v88, v94, v88
	v_add_f32_e32 v89, v89, v90
	s_nop 1
	v_permlane16_swap_b32_e32 v248, v250
	v_permlane16_swap_b32_e32 v249, v251
	global_store_dwordx4 v[96:97], v[248:251], off
	s_nop 1
	v_add_f32_e32 v92, v88, v89
	v_pk_fma_f32 v[90:91], v[82:83], 0.5, v[130:131] op_sel_hi:[1,0,1]
	v_pk_fma_f32 v[88:89], v[80:81], 0.5, v[128:129] op_sel_hi:[1,0,1]
	v_mul_f32_e32 v81, v91, v91
	v_mul_f32_e32 v80, v89, v89
	v_fmac_f32_e32 v80, v88, v88
	v_fmac_f32_e32 v81, v90, v90
	v_add_f32_e32 v80, v80, v81
	v_add_f32_e32 v82, v92, v80
	ds_bpermute_b32 v83, v132, v82
	v_cvt_pk_bf16_f32 v248, v84, v85
	v_cvt_pk_bf16_f32 v249, v86, v87
	global_store_dwordx4 v[98:99], v[84:87], off offset:512
	s_waitcnt lgkmcnt(0)
	v_add_f32_e32 v80, v82, v83
	ds_bpermute_b32 v81, v133, v80
	v_cvt_pk_bf16_f32 v250, v88, v89
	v_cvt_pk_bf16_f32 v251, v90, v91
	global_store_dwordx4 v[98:99], v[88:91], off offset:576
	s_nop 1
	v_permlane16_swap_b32_e32 v248, v250
	v_permlane16_swap_b32_e32 v249, v251
	global_store_dwordx4 v[96:97], v[248:251], off offset:256
	s_nop 1
	s_and_saveexec_b64 s[28:29], s[6:7]
	s_cbranch_execz .LBB0_502
	v_lshl_add_u64 v[82:83], v[190:191], 2, s[22:23]
	s_waitcnt lgkmcnt(0)
	v_add_f32_e32 v80, v80, v81
	global_atomic_add_f32 v[82:83], v80, off
.LBB0_502:
	s_or_b64 exec, exec, s[28:29]
	s_waitcnt lgkmcnt(0)
	v_lshlrev_b64 v[80:81], 11, v[188:189]
	v_lshl_add_u64 v[80:81], v[80:81], 0, v[182:183]
	v_pk_fma_f32 v[78:79], v[78:79], 0.5, v[150:151] op_sel_hi:[1,0,1]
	v_pk_fma_f32 v[76:77], v[76:77], 0.5, v[148:149] op_sel_hi:[1,0,1]
	v_lshl_add_u64 v[82:83], v[80:81], 2, s[12:13]
	global_store_dwordx4 v[82:83], v[76:79], off
	v_cvt_pk_bf16_f32 v248, v76, v77
	v_cvt_pk_bf16_f32 v249, v78, v79
	v_mul_f32_e32 v77, v77, v77
	v_fmac_f32_e32 v77, v76, v76
	v_mul_f32_e32 v76, v79, v79
	v_lshl_add_u64 v[80:81], v[80:81], 1, s[16:17]
	v_lshl_add_u64 v[80:81], v[80:81], 0, v[252:253]
	v_fmac_f32_e32 v76, v78, v78
	v_pk_fma_f32 v[74:75], v[74:75], 0.5, v[142:143] op_sel_hi:[1,0,1]
	v_pk_fma_f32 v[72:73], v[72:73], 0.5, v[140:141] op_sel_hi:[1,0,1]
	v_add_f32_e32 v78, v77, v76
	global_store_dwordx4 v[82:83], v[72:75], off offset:64
	v_cvt_pk_bf16_f32 v250, v72, v73
	v_pk_fma_f32 v[70:71], v[70:71], 0.5, v[126:127] op_sel_hi:[1,0,1]
	v_mul_f32_e32 v73, v73, v73
	v_fmac_f32_e32 v73, v72, v72
	v_mul_f32_e32 v72, v75, v75
	v_fmac_f32_e32 v72, v74, v74
	v_pk_fma_f32 v[68:69], v[68:69], 0.5, v[124:125] op_sel_hi:[1,0,1]
	v_cvt_pk_bf16_f32 v251, v74, v75
	v_add_f32_e32 v72, v73, v72
	v_mul_f32_e32 v73, v69, v69
	v_mul_f32_e32 v74, v71, v71
	v_fmac_f32_e32 v73, v68, v68
	v_fmac_f32_e32 v74, v70, v70
	v_add_f32_e32 v72, v78, v72
	v_add_f32_e32 v73, v73, v74
	s_nop 1
	v_permlane16_swap_b32_e32 v248, v250
	v_permlane16_swap_b32_e32 v249, v251
	global_store_dwordx4 v[80:81], v[248:251], off
	s_nop 1
	v_add_f32_e32 v76, v72, v73
	v_pk_fma_f32 v[74:75], v[66:67], 0.5, v[122:123] op_sel_hi:[1,0,1]
	v_pk_fma_f32 v[72:73], v[64:65], 0.5, v[120:121] op_sel_hi:[1,0,1]
	v_mul_f32_e32 v65, v75, v75
	v_mul_f32_e32 v64, v73, v73
	v_fmac_f32_e32 v64, v72, v72
	v_fmac_f32_e32 v65, v74, v74
	v_add_f32_e32 v64, v64, v65
	v_add_f32_e32 v66, v76, v64
	ds_bpermute_b32 v67, v132, v66
	v_cvt_pk_bf16_f32 v248, v68, v69
	v_cvt_pk_bf16_f32 v249, v70, v71
	global_store_dwordx4 v[82:83], v[68:71], off offset:512
	s_waitcnt lgkmcnt(0)
	v_add_f32_e32 v64, v66, v67
	ds_bpermute_b32 v65, v133, v64
	v_cvt_pk_bf16_f32 v250, v72, v73
	v_cvt_pk_bf16_f32 v251, v74, v75
	global_store_dwordx4 v[82:83], v[72:75], off offset:576
	s_nop 1
	v_permlane16_swap_b32_e32 v248, v250
	v_permlane16_swap_b32_e32 v249, v251
	global_store_dwordx4 v[80:81], v[248:251], off offset:256
	s_nop 1
	s_and_saveexec_b64 s[28:29], s[6:7]
	s_cbranch_execz .LBB0_504
	v_lshl_add_u64 v[66:67], v[188:189], 2, s[22:23]
	s_waitcnt lgkmcnt(0)
	v_add_f32_e32 v64, v64, v65
	global_atomic_add_f32 v[66:67], v64, off
.LBB0_504:
	s_or_b64 exec, exec, s[28:29]
	v_add_u32_e32 v126, 0x80, v186
	v_ashrrev_i32_e32 v127, 31, v126
	s_waitcnt lgkmcnt(0)
	v_lshlrev_b64 v[64:65], 13, v[126:127]
	v_lshl_add_u64 v[64:65], v[184:185], 0, v[64:65]
	global_load_dwordx4 v[128:131], v[64:65], off
	global_load_dwordx4 v[134:137], v[64:65], off offset:64
	global_load_dwordx4 v[116:119], v[64:65], off offset:512
	global_load_dwordx4 v[112:115], v[64:65], off offset:576
	v_add_u32_e32 v124, 0x90, v186
	v_ashrrev_i32_e32 v125, 31, v124
	v_lshlrev_b64 v[64:65], 13, v[124:125]
	v_add_u32_e32 v122, 0xa0, v186
	v_lshl_add_u64 v[64:65], v[184:185], 0, v[64:65]
	v_ashrrev_i32_e32 v123, 31, v122
	global_load_dwordx4 v[108:111], v[64:65], off
	global_load_dwordx4 v[104:107], v[64:65], off offset:64
	global_load_dwordx4 v[100:103], v[64:65], off offset:512
	global_load_dwordx4 v[96:99], v[64:65], off offset:576
	v_lshlrev_b64 v[64:65], 13, v[122:123]
	v_add_u32_e32 v120, 0xb0, v186
	v_lshl_add_u64 v[64:65], v[184:185], 0, v[64:65]
	v_ashrrev_i32_e32 v121, 31, v120
	global_load_dwordx4 v[92:95], v[64:65], off
	global_load_dwordx4 v[88:91], v[64:65], off offset:64
	global_load_dwordx4 v[80:83], v[64:65], off offset:512
	global_load_dwordx4 v[72:75], v[64:65], off offset:576
	v_lshlrev_b64 v[64:65], 13, v[120:121]
	v_lshl_add_u64 v[64:65], v[184:185], 0, v[64:65]
	global_load_dwordx4 v[84:87], v[64:65], off
	global_load_dwordx4 v[76:79], v[64:65], off offset:64
	global_load_dwordx4 v[68:71], v[64:65], off offset:512
	s_nop 0
	global_load_dwordx4 v[64:67], v[64:65], off offset:576
	v_lshlrev_b64 v[138:139], 11, v[126:127]
	v_lshl_add_u64 v[138:139], v[138:139], 0, v[182:183]
	s_waitcnt vmcnt(15)
	v_pk_fma_f32 v[62:63], v[62:63], 0.5, v[130:131] op_sel_hi:[1,0,1]
	v_pk_fma_f32 v[60:61], v[60:61], 0.5, v[128:129] op_sel_hi:[1,0,1]
	v_lshl_add_u64 v[128:129], v[138:139], 2, s[12:13]
	global_store_dwordx4 v[128:129], v[60:63], off
	v_cvt_pk_bf16_f32 v248, v60, v61
	v_cvt_pk_bf16_f32 v249, v62, v63
	v_mul_f32_e32 v61, v61, v61
	v_fmac_f32_e32 v61, v60, v60
	v_mul_f32_e32 v60, v63, v63
	v_lshl_add_u64 v[138:139], v[138:139], 1, s[16:17]
	v_lshl_add_u64 v[138:139], v[138:139], 0, v[252:253]
	v_fmac_f32_e32 v60, v62, v62
	s_waitcnt vmcnt(15)
	v_pk_fma_f32 v[58:59], v[58:59], 0.5, v[136:137] op_sel_hi:[1,0,1]
	v_pk_fma_f32 v[56:57], v[56:57], 0.5, v[134:135] op_sel_hi:[1,0,1]
	v_add_f32_e32 v62, v61, v60
	global_store_dwordx4 v[128:129], v[56:59], off offset:64
	v_cvt_pk_bf16_f32 v250, v56, v57
	v_cvt_pk_bf16_f32 v251, v58, v59
	v_mul_f32_e32 v57, v57, v57
	v_fmac_f32_e32 v57, v56, v56
	v_mul_f32_e32 v56, v59, v59
	v_fmac_f32_e32 v56, v58, v58
	v_add_f32_e32 v56, v57, v56
	s_waitcnt vmcnt(15)
	v_pk_fma_f32 v[54:55], v[54:55], 0.5, v[118:119] op_sel_hi:[1,0,1]
	v_pk_fma_f32 v[52:53], v[52:53], 0.5, v[116:117] op_sel_hi:[1,0,1]
	s_nop 1
	v_permlane16_swap_b32_e32 v248, v250
	v_permlane16_swap_b32_e32 v249, v251
	global_store_dwordx4 v[138:139], v[248:251], off
	s_nop 1
	v_add_f32_e32 v58, v62, v56
	global_store_dwordx4 v[128:129], v[52:55], off offset:512
	v_cvt_pk_bf16_f32 v248, v52, v53
	v_cvt_pk_bf16_f32 v249, v54, v55
	v_mul_f32_e32 v53, v53, v53
	v_fmac_f32_e32 v53, v52, v52
	v_mul_f32_e32 v52, v55, v55
	v_fmac_f32_e32 v52, v54, v54
	v_add_f32_e32 v52, v53, v52
	s_waitcnt vmcnt(16)
	v_pk_fma_f32 v[50:51], v[50:51], 0.5, v[114:115] op_sel_hi:[1,0,1]
	v_pk_fma_f32 v[48:49], v[48:49], 0.5, v[112:113] op_sel_hi:[1,0,1]
	v_add_f32_e32 v54, v58, v52
	global_store_dwordx4 v[128:129], v[48:51], off offset:576
	v_cvt_pk_bf16_f32 v250, v48, v49
	v_cvt_pk_bf16_f32 v251, v50, v51
	v_mul_f32_e32 v49, v49, v49
	v_fmac_f32_e32 v49, v48, v48
	v_mul_f32_e32 v48, v51, v51
	v_fmac_f32_e32 v48, v50, v50
	v_add_f32_e32 v48, v49, v48
	v_add_f32_e32 v48, v54, v48
	ds_bpermute_b32 v49, v132, v48
	s_nop 1
	v_permlane16_swap_b32_e32 v248, v250
	v_permlane16_swap_b32_e32 v249, v251
	global_store_dwordx4 v[138:139], v[248:251], off offset:256
	s_nop 1
	s_waitcnt lgkmcnt(0)
	v_add_f32_e32 v48, v48, v49
	ds_bpermute_b32 v49, v133, v48
	s_and_saveexec_b64 s[28:29], s[6:7]
	s_cbranch_execz .LBB0_506
	v_lshl_add_u64 v[50:51], v[126:127], 2, s[22:23]
	s_waitcnt lgkmcnt(0)
	v_add_f32_e32 v48, v48, v49
	global_atomic_add_f32 v[50:51], v48, off
.LBB0_506:
	s_or_b64 exec, exec, s[28:29]
	s_waitcnt lgkmcnt(0)
	v_lshlrev_b64 v[48:49], 11, v[124:125]
	v_lshl_add_u64 v[48:49], v[48:49], 0, v[182:183]
	s_waitcnt vmcnt(17)
	v_pk_fma_f32 v[46:47], v[46:47], 0.5, v[110:111] op_sel_hi:[1,0,1]
	v_pk_fma_f32 v[44:45], v[44:45], 0.5, v[108:109] op_sel_hi:[1,0,1]
	v_lshl_add_u64 v[50:51], v[48:49], 2, s[12:13]
	global_store_dwordx4 v[50:51], v[44:47], off
	v_cvt_pk_bf16_f32 v248, v44, v45
	v_cvt_pk_bf16_f32 v249, v46, v47
	v_mul_f32_e32 v45, v45, v45
	v_fmac_f32_e32 v45, v44, v44
	v_mul_f32_e32 v44, v47, v47
	v_lshl_add_u64 v[48:49], v[48:49], 1, s[16:17]
	v_lshl_add_u64 v[48:49], v[48:49], 0, v[252:253]
	v_fmac_f32_e32 v44, v46, v46
	s_waitcnt vmcnt(17)
	v_pk_fma_f32 v[42:43], v[42:43], 0.5, v[106:107] op_sel_hi:[1,0,1]
	v_pk_fma_f32 v[40:41], v[40:41], 0.5, v[104:105] op_sel_hi:[1,0,1]
	v_add_f32_e32 v46, v45, v44
	global_store_dwordx4 v[50:51], v[40:43], off offset:64
	v_cvt_pk_bf16_f32 v250, v40, v41
	s_waitcnt vmcnt(17)
	v_pk_fma_f32 v[38:39], v[38:39], 0.5, v[102:103] op_sel_hi:[1,0,1]
	v_mul_f32_e32 v41, v41, v41
	v_fmac_f32_e32 v41, v40, v40
	v_mul_f32_e32 v40, v43, v43
	v_fmac_f32_e32 v40, v42, v42
	v_pk_fma_f32 v[36:37], v[36:37], 0.5, v[100:101] op_sel_hi:[1,0,1]
	v_cvt_pk_bf16_f32 v251, v42, v43
	v_add_f32_e32 v40, v41, v40
	v_mul_f32_e32 v41, v37, v37
	v_mul_f32_e32 v42, v39, v39
	v_fmac_f32_e32 v41, v36, v36
	v_fmac_f32_e32 v42, v38, v38
	v_add_f32_e32 v40, v46, v40
	v_add_f32_e32 v41, v41, v42
	s_nop 1
	v_permlane16_swap_b32_e32 v248, v250
	v_permlane16_swap_b32_e32 v249, v251
	global_store_dwordx4 v[48:49], v[248:251], off
	s_nop 1
	v_add_f32_e32 v44, v40, v41
	s_waitcnt vmcnt(17)
	v_pk_fma_f32 v[42:43], v[34:35], 0.5, v[98:99] op_sel_hi:[1,0,1]
	v_pk_fma_f32 v[40:41], v[32:33], 0.5, v[96:97] op_sel_hi:[1,0,1]
	v_mul_f32_e32 v33, v43, v43
	v_mul_f32_e32 v32, v41, v41
	v_fmac_f32_e32 v32, v40, v40
	v_fmac_f32_e32 v33, v42, v42
	v_add_f32_e32 v32, v32, v33
	v_add_f32_e32 v34, v44, v32
	ds_bpermute_b32 v35, v132, v34
	v_cvt_pk_bf16_f32 v248, v36, v37
	v_cvt_pk_bf16_f32 v249, v38, v39
	global_store_dwordx4 v[50:51], v[36:39], off offset:512
	s_waitcnt lgkmcnt(0)
	v_add_f32_e32 v32, v34, v35
	ds_bpermute_b32 v33, v133, v32
	v_cvt_pk_bf16_f32 v250, v40, v41
	v_cvt_pk_bf16_f32 v251, v42, v43
	global_store_dwordx4 v[50:51], v[40:43], off offset:576
	s_nop 1
	v_permlane16_swap_b32_e32 v248, v250
	v_permlane16_swap_b32_e32 v249, v251
	global_store_dwordx4 v[48:49], v[248:251], off offset:256
	s_nop 1
	s_and_saveexec_b64 s[28:29], s[6:7]
	s_cbranch_execz .LBB0_508
	v_lshl_add_u64 v[34:35], v[124:125], 2, s[22:23]
	s_waitcnt lgkmcnt(0)
	v_add_f32_e32 v32, v32, v33
	global_atomic_add_f32 v[34:35], v32, off
.LBB0_508:
	s_or_b64 exec, exec, s[28:29]
	s_waitcnt lgkmcnt(0)
	v_lshlrev_b64 v[32:33], 11, v[122:123]
	v_lshl_add_u64 v[32:33], v[32:33], 0, v[182:183]
	s_waitcnt vmcnt(19)
	v_pk_fma_f32 v[30:31], v[30:31], 0.5, v[94:95] op_sel_hi:[1,0,1]
	v_pk_fma_f32 v[28:29], v[28:29], 0.5, v[92:93] op_sel_hi:[1,0,1]
	v_lshl_add_u64 v[34:35], v[32:33], 2, s[12:13]
	global_store_dwordx4 v[34:35], v[28:31], off
	v_cvt_pk_bf16_f32 v248, v28, v29
	v_cvt_pk_bf16_f32 v249, v30, v31
	v_mul_f32_e32 v29, v29, v29
	v_fmac_f32_e32 v29, v28, v28
	v_mul_f32_e32 v28, v31, v31
	v_lshl_add_u64 v[32:33], v[32:33], 1, s[16:17]
	v_lshl_add_u64 v[32:33], v[32:33], 0, v[252:253]
	v_fmac_f32_e32 v28, v30, v30
	s_waitcnt vmcnt(19)
	v_pk_fma_f32 v[26:27], v[26:27], 0.5, v[90:91] op_sel_hi:[1,0,1]
	v_pk_fma_f32 v[24:25], v[24:25], 0.5, v[88:89] op_sel_hi:[1,0,1]
	v_add_f32_e32 v30, v29, v28
	global_store_dwordx4 v[34:35], v[24:27], off offset:64
	v_cvt_pk_bf16_f32 v250, v24, v25
	s_waitcnt vmcnt(19)
	v_pk_fma_f32 v[22:23], v[22:23], 0.5, v[82:83] op_sel_hi:[1,0,1]
	v_mul_f32_e32 v25, v25, v25
	v_fmac_f32_e32 v25, v24, v24
	v_mul_f32_e32 v24, v27, v27
	v_fmac_f32_e32 v24, v26, v26
	v_pk_fma_f32 v[20:21], v[20:21], 0.5, v[80:81] op_sel_hi:[1,0,1]
	v_cvt_pk_bf16_f32 v251, v26, v27
	v_add_f32_e32 v24, v25, v24
	v_mul_f32_e32 v25, v21, v21
	v_mul_f32_e32 v26, v23, v23
	v_fmac_f32_e32 v25, v20, v20
	v_fmac_f32_e32 v26, v22, v22
	v_add_f32_e32 v24, v30, v24
	v_add_f32_e32 v25, v25, v26
	s_nop 1
	v_permlane16_swap_b32_e32 v248, v250
	v_permlane16_swap_b32_e32 v249, v251
	global_store_dwordx4 v[32:33], v[248:251], off
	s_nop 1
	v_add_f32_e32 v28, v24, v25
	s_waitcnt vmcnt(19)
	v_pk_fma_f32 v[26:27], v[18:19], 0.5, v[74:75] op_sel_hi:[1,0,1]
	v_pk_fma_f32 v[24:25], v[16:17], 0.5, v[72:73] op_sel_hi:[1,0,1]
	v_mul_f32_e32 v17, v27, v27
	v_mul_f32_e32 v16, v25, v25
	v_fmac_f32_e32 v16, v24, v24
	v_fmac_f32_e32 v17, v26, v26
	v_add_f32_e32 v16, v16, v17
	v_add_f32_e32 v18, v28, v16
	ds_bpermute_b32 v19, v132, v18
	v_cvt_pk_bf16_f32 v248, v20, v21
	v_cvt_pk_bf16_f32 v249, v22, v23
	global_store_dwordx4 v[34:35], v[20:23], off offset:512
	s_waitcnt lgkmcnt(0)
	v_add_f32_e32 v16, v18, v19
	ds_bpermute_b32 v17, v133, v16
	v_cvt_pk_bf16_f32 v250, v24, v25
	v_cvt_pk_bf16_f32 v251, v26, v27
	global_store_dwordx4 v[34:35], v[24:27], off offset:576
	s_nop 1
	v_permlane16_swap_b32_e32 v248, v250
	v_permlane16_swap_b32_e32 v249, v251
	global_store_dwordx4 v[32:33], v[248:251], off offset:256
	s_nop 1
	s_and_saveexec_b64 s[28:29], s[6:7]
	s_cbranch_execz .LBB0_510
	v_lshl_add_u64 v[18:19], v[122:123], 2, s[22:23]
	s_waitcnt lgkmcnt(0)
	v_add_f32_e32 v16, v16, v17
	global_atomic_add_f32 v[18:19], v16, off
.LBB0_510:
	s_or_b64 exec, exec, s[28:29]
	s_waitcnt lgkmcnt(0)
	v_lshlrev_b64 v[16:17], 11, v[120:121]
	v_lshl_add_u64 v[16:17], v[16:17], 0, v[182:183]
	s_waitcnt vmcnt(21)
	v_pk_fma_f32 v[14:15], v[14:15], 0.5, v[86:87] op_sel_hi:[1,0,1]
	v_pk_fma_f32 v[12:13], v[12:13], 0.5, v[84:85] op_sel_hi:[1,0,1]
	v_lshl_add_u64 v[18:19], v[16:17], 2, s[12:13]
	global_store_dwordx4 v[18:19], v[12:15], off
	v_cvt_pk_bf16_f32 v248, v12, v13
	v_cvt_pk_bf16_f32 v249, v14, v15
	v_mul_f32_e32 v13, v13, v13
	v_fmac_f32_e32 v13, v12, v12
	v_mul_f32_e32 v12, v15, v15
	v_lshl_add_u64 v[16:17], v[16:17], 1, s[16:17]
	v_lshl_add_u64 v[16:17], v[16:17], 0, v[252:253]
	v_fmac_f32_e32 v12, v14, v14
	s_waitcnt vmcnt(21)
	v_pk_fma_f32 v[10:11], v[10:11], 0.5, v[78:79] op_sel_hi:[1,0,1]
	v_pk_fma_f32 v[8:9], v[8:9], 0.5, v[76:77] op_sel_hi:[1,0,1]
	v_add_f32_e32 v14, v13, v12
	global_store_dwordx4 v[18:19], v[8:11], off offset:64
	v_cvt_pk_bf16_f32 v250, v8, v9
	s_waitcnt vmcnt(21)
	v_pk_fma_f32 v[6:7], v[6:7], 0.5, v[70:71] op_sel_hi:[1,0,1]
	v_mul_f32_e32 v9, v9, v9
	v_fmac_f32_e32 v9, v8, v8
	v_mul_f32_e32 v8, v11, v11
	v_fmac_f32_e32 v8, v10, v10
	v_pk_fma_f32 v[4:5], v[4:5], 0.5, v[68:69] op_sel_hi:[1,0,1]
	v_cvt_pk_bf16_f32 v251, v10, v11
	v_add_f32_e32 v8, v9, v8
	v_mul_f32_e32 v9, v5, v5
	v_mul_f32_e32 v10, v7, v7
	v_fmac_f32_e32 v9, v4, v4
	v_fmac_f32_e32 v10, v6, v6
	v_add_f32_e32 v8, v14, v8
	v_add_f32_e32 v9, v9, v10
	s_nop 1
	v_permlane16_swap_b32_e32 v248, v250
	v_permlane16_swap_b32_e32 v249, v251
	global_store_dwordx4 v[16:17], v[248:251], off
	s_nop 1
	v_add_f32_e32 v12, v8, v9
	s_waitcnt vmcnt(21)
	v_pk_fma_f32 v[10:11], v[2:3], 0.5, v[66:67] op_sel_hi:[1,0,1]
	v_pk_fma_f32 v[8:9], v[0:1], 0.5, v[64:65] op_sel_hi:[1,0,1]
	v_mul_f32_e32 v1, v11, v11
	v_mul_f32_e32 v0, v9, v9
	v_fmac_f32_e32 v0, v8, v8
	v_fmac_f32_e32 v1, v10, v10
	v_add_f32_e32 v0, v0, v1
	v_add_f32_e32 v2, v12, v0
	ds_bpermute_b32 v3, v132, v2
	v_cvt_pk_bf16_f32 v248, v4, v5
	v_cvt_pk_bf16_f32 v249, v6, v7
	global_store_dwordx4 v[18:19], v[4:7], off offset:512
	s_waitcnt lgkmcnt(0)
	v_add_f32_e32 v0, v2, v3
	ds_bpermute_b32 v1, v133, v0
	v_cvt_pk_bf16_f32 v250, v8, v9
	v_cvt_pk_bf16_f32 v251, v10, v11
	global_store_dwordx4 v[18:19], v[8:11], off offset:576
	s_nop 1
	v_permlane16_swap_b32_e32 v248, v250
	v_permlane16_swap_b32_e32 v249, v251
	global_store_dwordx4 v[16:17], v[248:251], off offset:256
	s_nop 1
	s_and_saveexec_b64 s[28:29], s[6:7]
	s_cbranch_execz .LBB0_512
	v_lshl_add_u64 v[2:3], v[120:121], 2, s[22:23]
	s_waitcnt lgkmcnt(0)
	v_add_f32_e32 v0, v0, v1
	global_atomic_add_f32 v[2:3], v0, off
